# hand-written EpiSc epilogue without an initial vmcnt wait (no loads in it)
# speedup vs baseline: 1.0063x; 1.0063x over previous
.LBB0_1312:
	v_lshl_add_u32 v161, s36, 8, v144
	v_lshl_add_u32 v162, s24, 8, v146
	v_lshlrev_b32_e32 v163, 11, v161
	v_lshl_add_u32 v163, v162, 1, v163
	v_mbcnt_lo_u32_b32 v158, -1, 0
	v_mbcnt_hi_u32_b32 v158, -1, v158
	v_lshrrev_b32_e32 v159, 4, v158
	v_lshlrev_b32_e32 v160, 1, v159
	v_and_b32_e32 v160, 2, v160
	v_lshrrev_b32_e32 v159, 1, v159
	v_or_b32_e32 v160, v160, v159
	v_lshl_add_u32 v164, v160, 4, v161
	s_lshl_b32 s38, s24, 4
	s_lshl_b32 s39, s71, 2
	s_add_i32 s38, s38, s39
	v_lshl_add_u32 v164, v164, 6, s38
	v_add_u32_e32 v165, 0x2000, v164
	v_mov_b32_e32 v150, 0x3fb8aa3b
	v_mov_b32_e32 v151, 0x3fb8aa3b
	v_mov_b32_e32 v166, v163
	v_add_u32_e32 v167, 0x8000, v163
	v_add_u32_e32 v168, 0x10000, v163
	v_add_u32_e32 v169, 0x18000, v163
	v_add_u32_e32 v170, 0x40000, v163
	v_add_u32_e32 v171, 0x48000, v163
	v_add_u32_e32 v172, 0x50000, v163
	v_add_u32_e32 v173, 0x58000, v163
	v_pk_mul_f32 v[124:125], v[124:125], v[150:151]
	v_pk_mul_f32 v[126:127], v[126:127], v[150:151]
	v_pk_mul_f32 v[120:121], v[120:121], v[150:151]
	v_pk_mul_f32 v[122:123], v[122:123], v[150:151]
	v_pk_mul_f32 v[116:117], v[116:117], v[150:151]
	v_pk_mul_f32 v[118:119], v[118:119], v[150:151]
	v_pk_mul_f32 v[112:113], v[112:113], v[150:151]
	v_pk_mul_f32 v[114:115], v[114:115], v[150:151]
	v_exp_f32_e32 v124, v124
	v_exp_f32_e32 v125, v125
	v_exp_f32_e32 v126, v126
	v_exp_f32_e32 v127, v127
	v_exp_f32_e32 v120, v120
	v_exp_f32_e32 v121, v121
	v_exp_f32_e32 v122, v122
	v_exp_f32_e32 v123, v123
	v_exp_f32_e32 v116, v116
	v_exp_f32_e32 v117, v117
	v_exp_f32_e32 v118, v118
	v_exp_f32_e32 v119, v119
	v_exp_f32_e32 v112, v112
	v_exp_f32_e32 v113, v113
	v_exp_f32_e32 v114, v114
	v_exp_f32_e32 v115, v115
	s_nop 0
	v_pk_add_f32 v[156:157], v[124:125], v[126:127]
	v_pk_add_f32 v[156:157], v[156:157], v[120:121]
	v_pk_add_f32 v[156:157], v[156:157], v[122:123]
	v_pk_add_f32 v[156:157], v[156:157], v[116:117]
	v_pk_add_f32 v[156:157], v[156:157], v[118:119]
	v_pk_add_f32 v[156:157], v[156:157], v[112:113]
	v_pk_add_f32 v[156:157], v[156:157], v[114:115]
	v_add_f32_e32 v152, v156, v157
	v_cvt_pk_bf16_f32 v124, v124, v125
	v_cvt_pk_bf16_f32 v125, v126, v127
	v_cvt_pk_bf16_f32 v126, v120, v121
	v_cvt_pk_bf16_f32 v127, v122, v123
	global_store_dwordx4 v166, v[124:127], s[16:17]
	v_cvt_pk_bf16_f32 v116, v116, v117
	v_cvt_pk_bf16_f32 v117, v118, v119
	v_cvt_pk_bf16_f32 v118, v112, v113
	v_cvt_pk_bf16_f32 v119, v114, v115
	global_store_dwordx4 v166, v[116:119], s[16:17] offset:256
	v_pk_mul_f32 v[108:109], v[108:109], v[150:151]
	v_pk_mul_f32 v[110:111], v[110:111], v[150:151]
	v_pk_mul_f32 v[104:105], v[104:105], v[150:151]
	v_pk_mul_f32 v[106:107], v[106:107], v[150:151]
	v_pk_mul_f32 v[100:101], v[100:101], v[150:151]
	v_pk_mul_f32 v[102:103], v[102:103], v[150:151]
	v_pk_mul_f32 v[96:97], v[96:97], v[150:151]
	v_pk_mul_f32 v[98:99], v[98:99], v[150:151]
	v_exp_f32_e32 v108, v108
	v_exp_f32_e32 v109, v109
	v_exp_f32_e32 v110, v110
	v_exp_f32_e32 v111, v111
	v_exp_f32_e32 v104, v104
	v_exp_f32_e32 v105, v105
	v_exp_f32_e32 v106, v106
	v_exp_f32_e32 v107, v107
	v_exp_f32_e32 v100, v100
	v_exp_f32_e32 v101, v101
	v_exp_f32_e32 v102, v102
	v_exp_f32_e32 v103, v103
	v_exp_f32_e32 v96, v96
	v_exp_f32_e32 v97, v97
	v_exp_f32_e32 v98, v98
	v_exp_f32_e32 v99, v99
	s_nop 0
	v_pk_add_f32 v[156:157], v[108:109], v[110:111]
	v_pk_add_f32 v[156:157], v[156:157], v[104:105]
	v_pk_add_f32 v[156:157], v[156:157], v[106:107]
	v_pk_add_f32 v[156:157], v[156:157], v[100:101]
	v_pk_add_f32 v[156:157], v[156:157], v[102:103]
	v_pk_add_f32 v[156:157], v[156:157], v[96:97]
	v_pk_add_f32 v[156:157], v[156:157], v[98:99]
	v_add_f32_e32 v153, v156, v157
	v_cvt_pk_bf16_f32 v108, v108, v109
	v_cvt_pk_bf16_f32 v109, v110, v111
	v_cvt_pk_bf16_f32 v110, v104, v105
	v_cvt_pk_bf16_f32 v111, v106, v107
	global_store_dwordx4 v167, v[108:111], s[16:17]
	v_cvt_pk_bf16_f32 v100, v100, v101
	v_cvt_pk_bf16_f32 v101, v102, v103
	v_cvt_pk_bf16_f32 v102, v96, v97
	v_cvt_pk_bf16_f32 v103, v98, v99
	global_store_dwordx4 v167, v[100:103], s[16:17] offset:256
	v_pk_mul_f32 v[92:93], v[92:93], v[150:151]
	v_pk_mul_f32 v[94:95], v[94:95], v[150:151]
	v_pk_mul_f32 v[88:89], v[88:89], v[150:151]
	v_pk_mul_f32 v[90:91], v[90:91], v[150:151]
	v_pk_mul_f32 v[84:85], v[84:85], v[150:151]
	v_pk_mul_f32 v[86:87], v[86:87], v[150:151]
	v_pk_mul_f32 v[80:81], v[80:81], v[150:151]
	v_pk_mul_f32 v[82:83], v[82:83], v[150:151]
	v_exp_f32_e32 v92, v92
	v_exp_f32_e32 v93, v93
	v_exp_f32_e32 v94, v94
	v_exp_f32_e32 v95, v95
	v_exp_f32_e32 v88, v88
	v_exp_f32_e32 v89, v89
	v_exp_f32_e32 v90, v90
	v_exp_f32_e32 v91, v91
	v_exp_f32_e32 v84, v84
	v_exp_f32_e32 v85, v85
	v_exp_f32_e32 v86, v86
	v_exp_f32_e32 v87, v87
	v_exp_f32_e32 v80, v80
	v_exp_f32_e32 v81, v81
	v_exp_f32_e32 v82, v82
	v_exp_f32_e32 v83, v83
	s_nop 0
	v_pk_add_f32 v[156:157], v[92:93], v[94:95]
	v_pk_add_f32 v[156:157], v[156:157], v[88:89]
	v_pk_add_f32 v[156:157], v[156:157], v[90:91]
	v_pk_add_f32 v[156:157], v[156:157], v[84:85]
	v_pk_add_f32 v[156:157], v[156:157], v[86:87]
	v_pk_add_f32 v[156:157], v[156:157], v[80:81]
	v_pk_add_f32 v[156:157], v[156:157], v[82:83]
	v_add_f32_e32 v154, v156, v157
	v_cvt_pk_bf16_f32 v92, v92, v93
	v_cvt_pk_bf16_f32 v93, v94, v95
	v_cvt_pk_bf16_f32 v94, v88, v89
	v_cvt_pk_bf16_f32 v95, v90, v91
	global_store_dwordx4 v168, v[92:95], s[16:17]
	v_cvt_pk_bf16_f32 v84, v84, v85
	v_cvt_pk_bf16_f32 v85, v86, v87
	v_cvt_pk_bf16_f32 v86, v80, v81
	v_cvt_pk_bf16_f32 v87, v82, v83
	global_store_dwordx4 v168, v[84:87], s[16:17] offset:256
	v_pk_mul_f32 v[76:77], v[76:77], v[150:151]
	v_pk_mul_f32 v[78:79], v[78:79], v[150:151]
	v_pk_mul_f32 v[72:73], v[72:73], v[150:151]
	v_pk_mul_f32 v[74:75], v[74:75], v[150:151]
	v_pk_mul_f32 v[68:69], v[68:69], v[150:151]
	v_pk_mul_f32 v[70:71], v[70:71], v[150:151]
	v_pk_mul_f32 v[64:65], v[64:65], v[150:151]
	v_pk_mul_f32 v[66:67], v[66:67], v[150:151]
	v_exp_f32_e32 v76, v76
	v_exp_f32_e32 v77, v77
	v_exp_f32_e32 v78, v78
	v_exp_f32_e32 v79, v79
	v_exp_f32_e32 v72, v72
	v_exp_f32_e32 v73, v73
	v_exp_f32_e32 v74, v74
	v_exp_f32_e32 v75, v75
	v_exp_f32_e32 v68, v68
	v_exp_f32_e32 v69, v69
	v_exp_f32_e32 v70, v70
	v_exp_f32_e32 v71, v71
	v_exp_f32_e32 v64, v64
	v_exp_f32_e32 v65, v65
	v_exp_f32_e32 v66, v66
	v_exp_f32_e32 v67, v67
	s_nop 0
	v_pk_add_f32 v[156:157], v[76:77], v[78:79]
	v_pk_add_f32 v[156:157], v[156:157], v[72:73]
	v_pk_add_f32 v[156:157], v[156:157], v[74:75]
	v_pk_add_f32 v[156:157], v[156:157], v[68:69]
	v_pk_add_f32 v[156:157], v[156:157], v[70:71]
	v_pk_add_f32 v[156:157], v[156:157], v[64:65]
	v_pk_add_f32 v[156:157], v[156:157], v[66:67]
	v_add_f32_e32 v155, v156, v157
	v_cvt_pk_bf16_f32 v76, v76, v77
	v_cvt_pk_bf16_f32 v77, v78, v79
	v_cvt_pk_bf16_f32 v78, v72, v73
	v_cvt_pk_bf16_f32 v79, v74, v75
	global_store_dwordx4 v169, v[76:79], s[16:17]
	v_cvt_pk_bf16_f32 v68, v68, v69
	v_cvt_pk_bf16_f32 v69, v70, v71
	v_cvt_pk_bf16_f32 v70, v64, v65
	v_cvt_pk_bf16_f32 v71, v66, v67
	global_store_dwordx4 v169, v[68:71], s[16:17] offset:256
	s_nop 1
	v_permlane32_swap_b32_e32 v152, v153
	v_permlane32_swap_b32_e32 v154, v155
	v_add_f32_e32 v152, v152, v153
	v_add_f32_e32 v154, v154, v155
	s_nop 1
	v_permlane16_swap_b32_e32 v152, v154
	v_add_f32_e32 v152, v152, v154
	global_store_dword v164, v152, s[18:19]
	v_pk_mul_f32 v[60:61], v[60:61], v[150:151]
	v_pk_mul_f32 v[62:63], v[62:63], v[150:151]
	v_pk_mul_f32 v[56:57], v[56:57], v[150:151]
	v_pk_mul_f32 v[58:59], v[58:59], v[150:151]
	v_pk_mul_f32 v[52:53], v[52:53], v[150:151]
	v_pk_mul_f32 v[54:55], v[54:55], v[150:151]
	v_pk_mul_f32 v[48:49], v[48:49], v[150:151]
	v_pk_mul_f32 v[50:51], v[50:51], v[150:151]
	v_exp_f32_e32 v60, v60
	v_exp_f32_e32 v61, v61
	v_exp_f32_e32 v62, v62
	v_exp_f32_e32 v63, v63
	v_exp_f32_e32 v56, v56
	v_exp_f32_e32 v57, v57
	v_exp_f32_e32 v58, v58
	v_exp_f32_e32 v59, v59
	v_exp_f32_e32 v52, v52
	v_exp_f32_e32 v53, v53
	v_exp_f32_e32 v54, v54
	v_exp_f32_e32 v55, v55
	v_exp_f32_e32 v48, v48
	v_exp_f32_e32 v49, v49
	v_exp_f32_e32 v50, v50
	v_exp_f32_e32 v51, v51
	s_nop 0
	v_pk_add_f32 v[156:157], v[60:61], v[62:63]
	v_pk_add_f32 v[156:157], v[156:157], v[56:57]
	v_pk_add_f32 v[156:157], v[156:157], v[58:59]
	v_pk_add_f32 v[156:157], v[156:157], v[52:53]
	v_pk_add_f32 v[156:157], v[156:157], v[54:55]
	v_pk_add_f32 v[156:157], v[156:157], v[48:49]
	v_pk_add_f32 v[156:157], v[156:157], v[50:51]
	v_add_f32_e32 v152, v156, v157
	v_cvt_pk_bf16_f32 v60, v60, v61
	v_cvt_pk_bf16_f32 v61, v62, v63
	v_cvt_pk_bf16_f32 v62, v56, v57
	v_cvt_pk_bf16_f32 v63, v58, v59
	global_store_dwordx4 v170, v[60:63], s[16:17]
	v_cvt_pk_bf16_f32 v52, v52, v53
	v_cvt_pk_bf16_f32 v53, v54, v55
	v_cvt_pk_bf16_f32 v54, v48, v49
	v_cvt_pk_bf16_f32 v55, v50, v51
	global_store_dwordx4 v170, v[52:55], s[16:17] offset:256
	v_pk_mul_f32 v[44:45], v[44:45], v[150:151]
	v_pk_mul_f32 v[46:47], v[46:47], v[150:151]
	v_pk_mul_f32 v[40:41], v[40:41], v[150:151]
	v_pk_mul_f32 v[42:43], v[42:43], v[150:151]
	v_pk_mul_f32 v[36:37], v[36:37], v[150:151]
	v_pk_mul_f32 v[38:39], v[38:39], v[150:151]
	v_pk_mul_f32 v[32:33], v[32:33], v[150:151]
	v_pk_mul_f32 v[34:35], v[34:35], v[150:151]
	v_exp_f32_e32 v44, v44
	v_exp_f32_e32 v45, v45
	v_exp_f32_e32 v46, v46
	v_exp_f32_e32 v47, v47
	v_exp_f32_e32 v40, v40
	v_exp_f32_e32 v41, v41
	v_exp_f32_e32 v42, v42
	v_exp_f32_e32 v43, v43
	v_exp_f32_e32 v36, v36
	v_exp_f32_e32 v37, v37
	v_exp_f32_e32 v38, v38
	v_exp_f32_e32 v39, v39
	v_exp_f32_e32 v32, v32
	v_exp_f32_e32 v33, v33
	v_exp_f32_e32 v34, v34
	v_exp_f32_e32 v35, v35
	s_nop 0
	v_pk_add_f32 v[156:157], v[44:45], v[46:47]
	v_pk_add_f32 v[156:157], v[156:157], v[40:41]
	v_pk_add_f32 v[156:157], v[156:157], v[42:43]
	v_pk_add_f32 v[156:157], v[156:157], v[36:37]
	v_pk_add_f32 v[156:157], v[156:157], v[38:39]
	v_pk_add_f32 v[156:157], v[156:157], v[32:33]
	v_pk_add_f32 v[156:157], v[156:157], v[34:35]
	v_add_f32_e32 v153, v156, v157
	v_cvt_pk_bf16_f32 v44, v44, v45
	v_cvt_pk_bf16_f32 v45, v46, v47
	v_cvt_pk_bf16_f32 v46, v40, v41
	v_cvt_pk_bf16_f32 v47, v42, v43
	global_store_dwordx4 v171, v[44:47], s[16:17]
	v_cvt_pk_bf16_f32 v36, v36, v37
	v_cvt_pk_bf16_f32 v37, v38, v39
	v_cvt_pk_bf16_f32 v38, v32, v33
	v_cvt_pk_bf16_f32 v39, v34, v35
	global_store_dwordx4 v171, v[36:39], s[16:17] offset:256
	v_pk_mul_f32 v[28:29], v[28:29], v[150:151]
	v_pk_mul_f32 v[30:31], v[30:31], v[150:151]
	v_pk_mul_f32 v[24:25], v[24:25], v[150:151]
	v_pk_mul_f32 v[26:27], v[26:27], v[150:151]
	v_pk_mul_f32 v[20:21], v[20:21], v[150:151]
	v_pk_mul_f32 v[22:23], v[22:23], v[150:151]
	v_pk_mul_f32 v[16:17], v[16:17], v[150:151]
	v_pk_mul_f32 v[18:19], v[18:19], v[150:151]
	v_exp_f32_e32 v28, v28
	v_exp_f32_e32 v29, v29
	v_exp_f32_e32 v30, v30
	v_exp_f32_e32 v31, v31
	v_exp_f32_e32 v24, v24
	v_exp_f32_e32 v25, v25
	v_exp_f32_e32 v26, v26
	v_exp_f32_e32 v27, v27
	v_exp_f32_e32 v20, v20
	v_exp_f32_e32 v21, v21
	v_exp_f32_e32 v22, v22
	v_exp_f32_e32 v23, v23
	v_exp_f32_e32 v16, v16
	v_exp_f32_e32 v17, v17
	v_exp_f32_e32 v18, v18
	v_exp_f32_e32 v19, v19
	s_nop 0
	v_pk_add_f32 v[156:157], v[28:29], v[30:31]
	v_pk_add_f32 v[156:157], v[156:157], v[24:25]
	v_pk_add_f32 v[156:157], v[156:157], v[26:27]
	v_pk_add_f32 v[156:157], v[156:157], v[20:21]
	v_pk_add_f32 v[156:157], v[156:157], v[22:23]
	v_pk_add_f32 v[156:157], v[156:157], v[16:17]
	v_pk_add_f32 v[156:157], v[156:157], v[18:19]
	v_add_f32_e32 v154, v156, v157
	v_cvt_pk_bf16_f32 v28, v28, v29
	v_cvt_pk_bf16_f32 v29, v30, v31
	v_cvt_pk_bf16_f32 v30, v24, v25
	v_cvt_pk_bf16_f32 v31, v26, v27
	global_store_dwordx4 v172, v[28:31], s[16:17]
	v_cvt_pk_bf16_f32 v20, v20, v21
	v_cvt_pk_bf16_f32 v21, v22, v23
	v_cvt_pk_bf16_f32 v22, v16, v17
	v_cvt_pk_bf16_f32 v23, v18, v19
	global_store_dwordx4 v172, v[20:23], s[16:17] offset:256
	v_pk_mul_f32 v[12:13], v[12:13], v[150:151]
	v_pk_mul_f32 v[14:15], v[14:15], v[150:151]
	v_pk_mul_f32 v[8:9], v[8:9], v[150:151]
	v_pk_mul_f32 v[10:11], v[10:11], v[150:151]
	v_pk_mul_f32 v[4:5], v[4:5], v[150:151]
	v_pk_mul_f32 v[6:7], v[6:7], v[150:151]
	v_pk_mul_f32 v[0:1], v[0:1], v[150:151]
	v_pk_mul_f32 v[2:3], v[2:3], v[150:151]
	v_exp_f32_e32 v12, v12
	v_exp_f32_e32 v13, v13
	v_exp_f32_e32 v14, v14
	v_exp_f32_e32 v15, v15
	v_exp_f32_e32 v8, v8
	v_exp_f32_e32 v9, v9
	v_exp_f32_e32 v10, v10
	v_exp_f32_e32 v11, v11
	v_exp_f32_e32 v4, v4
	v_exp_f32_e32 v5, v5
	v_exp_f32_e32 v6, v6
	v_exp_f32_e32 v7, v7
	v_exp_f32_e32 v0, v0
	v_exp_f32_e32 v1, v1
	v_exp_f32_e32 v2, v2
	v_exp_f32_e32 v3, v3
	s_nop 0
	v_pk_add_f32 v[156:157], v[12:13], v[14:15]
	v_pk_add_f32 v[156:157], v[156:157], v[8:9]
	v_pk_add_f32 v[156:157], v[156:157], v[10:11]
	v_pk_add_f32 v[156:157], v[156:157], v[4:5]
	v_pk_add_f32 v[156:157], v[156:157], v[6:7]
	v_pk_add_f32 v[156:157], v[156:157], v[0:1]
	v_pk_add_f32 v[156:157], v[156:157], v[2:3]
	v_add_f32_e32 v155, v156, v157
	v_cvt_pk_bf16_f32 v12, v12, v13
	v_cvt_pk_bf16_f32 v13, v14, v15
	v_cvt_pk_bf16_f32 v14, v8, v9
	v_cvt_pk_bf16_f32 v15, v10, v11
	global_store_dwordx4 v173, v[12:15], s[16:17]
	v_cvt_pk_bf16_f32 v4, v4, v5
	v_cvt_pk_bf16_f32 v5, v6, v7
	v_cvt_pk_bf16_f32 v6, v0, v1
	v_cvt_pk_bf16_f32 v7, v2, v3
	global_store_dwordx4 v173, v[4:7], s[16:17] offset:256
	s_nop 1
	v_permlane32_swap_b32_e32 v152, v153
	v_permlane32_swap_b32_e32 v154, v155
	v_add_f32_e32 v152, v152, v153
	v_add_f32_e32 v154, v154, v155
	s_nop 1
	v_permlane16_swap_b32_e32 v152, v154
	v_add_f32_e32 v152, v152, v154
	global_store_dword v165, v152, s[18:19]
	s_and_b64 vcc, exec, s[8:9]
	s_mov_b64 s[8:9], -1
	s_cbranch_vccnz .LBB0_1297
	s_and_b64 vcc, exec, s[0:1]
	s_cbranch_vccnz .LBB0_1296
	s_barrier
	s_branch .LBB0_1296
